# U-half row-sum reduction made transposing (34 instead of 64 VALU per token-slice; the U loop is VALU-issue bound)
# speedup vs baseline: 1.0082x; 1.0082x over previous
;     DEVI int* eidx() const { return (int*)(ws + WS_EIDX); }
; #define LAS __attribute__((address_space(3)))
;     const int n16 = lane & 15, kq = lane >> 4;
;     LAS u32x2_t* pl = (LAS u32x2_t*)wl;
;     if (PART != 2) {
;     int e[NTL]; float g[NTL], s_u[NTL], s_v[NTL];
; #pragma unroll
;     for (int t = 0; t < NTL; ++t) { e[t] = eidx[(size_t)r * 128 + (tbase + t) * 16 + n16]; g[t] = gwv[(size_t)r * 128 + (tbase + t) * 16 + n16]; }
; #pragma unroll
;     for (int t = 0; t < NTL; ++t) { s_u[t] = su[e[t]]; s_v[t] = sv[e[t]]; }
;     const unsigned char* up[NTL];
; #pragma unroll
;     for (int t = 0; t < NTL; ++t) up[t] = u8 + (size_t)e[t] * D + kq * 16;
;     const unsigned char* hp = h8 + (n16 < 8 ? (size_t)0 : (size_t)M * D) + (size_t)r * D + kq * 16;
;     f32x4_t acc[NTL];
; #pragma unroll
;     for (int t = 0; t < NTL; ++t) acc[t] = (f32x4_t){0.f, 0.f, 0.f, 0.f};
;     u32x4_t b0[NTL], b1[NTL];
; #pragma unroll
;     for (int t = 0; t < NTL; ++t) { b0[t] = *(const u32x4_t*)(up[t]); b1[t] = *(const u32x4_t*)(up[t] + 64); }
.LBB0_1084:
	s_or_b64 exec, exec, s[40:41]
	v_readlane_b32 s2, v253, 41
	s_mov_b64 s[6:7], s[74:75]
	s_mov_b64 s[4:5], s[72:73]
	s_mov_b32 s8, s2
	v_mov_b32_e32 v1, v210
	v_readlane_b32 s48, v252, 3
	s_mov_b32 s36, s68
	s_waitcnt lgkmcnt(0)
	s_barrier
	s_cmpk_gt_i32 s48, 0x3fff
	v_and_b32_e32 v116, 15, v1
	v_and_b32_e32 v102, -16, v1
	v_lshlrev_b32_e32 v100, 4, v1
	v_cmp_gt_u32_e64 s[2:3], 16, v1
	s_mul_hi_i32 s46, s8, 0x6c000
	s_mul_i32 s47, s8, 0x6c000
	v_ashrrev_i32_e32 v103, 31, v102
	v_cmp_gt_u32_e32 vcc, 8, v116
	v_lshl_add_u32 v117, v1, 3, s85
	v_ashrrev_i32_e32 v101, 31, v100
	s_cbranch_scc1 .LBB0_1124
	s_lshl_b32 s20, s34, 9
	s_lshl_b32 s21, s34, 10
	s_lshl_b32 s11, s8, 24
	s_add_u32 s56, s6, 0x1fa42100
	s_addc_u32 s57, s7, 0
	s_add_u32 s56, s56, s11
	s_addc_u32 s57, s57, 0
	s_mov_b32 s12, s56
	s_mov_b32 s13, s57
	s_lshl_b32 s11, s48, 9
	s_add_u32 s58, s6, 0x1b292100
	s_addc_u32 s59, s7, 0
	s_add_u32 s58, s58, s11
	s_addc_u32 s59, s59, 0
	s_lshl_b32 s11, s48, 10
	s_add_u32 s60, s6, 0x2fac2100
	s_addc_u32 s61, s7, 0
	s_add_u32 s60, s60, s11
	s_addc_u32 s61, s61, 0
	s_mov_b32 s40, 0xaaaaaaaa
	s_mov_b32 s41, 0xaaaaaaaa
	s_mov_b32 s42, 0xcccccccc
	s_mov_b32 s43, 0xcccccccc
	v_and_b32_e32 v2, 7, v1
	v_lshrrev_b32_e32 v3, 3, v1
	v_lshlrev_b32_e32 v4, 4, v2
	v_lshlrev_b32_e32 v5, 6, v3
	v_lshlrev_b32_e32 v6, 7, v3
	v_add3_u32 v6, v6, v4, s85
	v_mov_b32_e32 v8, 0x3d000000
	v_mov_b32_e32 v9, 0x3d000000
	v_mov_b32_e32 v118, 0
	v_mov_b32_e32 v119, 0
	ds_write_b32 v6, v118 offset:4
	ds_write_b32 v6, v118 offset:12
	ds_write_b32 v6, v118 offset:1028
	ds_write_b32 v6, v118 offset:1036
	ds_write_b32 v6, v118 offset:2052
	ds_write_b32 v6, v118 offset:2060
	ds_write_b32 v6, v118 offset:3076
	ds_write_b32 v6, v118 offset:3084
	ds_write_b32 v6, v118 offset:4100
	ds_write_b32 v6, v118 offset:4108
	ds_write_b32 v6, v118 offset:5124
	ds_write_b32 v6, v118 offset:5132
	ds_write_b32 v6, v118 offset:6148
	ds_write_b32 v6, v118 offset:6156
	ds_write_b32 v6, v118 offset:7172
	ds_write_b32 v6, v118 offset:7180
	global_load_dwordx4 v[84:87], v5, s[58:59] offset:0
	global_load_dwordx4 v[88:91], v5, s[58:59] offset:16
	global_load_dwordx4 v[92:95], v5, s[58:59] offset:32
	global_load_dwordx4 v[96:99], v5, s[58:59] offset:48
	s_waitcnt vmcnt(0)
	v_lshl_add_u32 v68, v84, 10, v4
	v_lshl_add_u32 v69, v85, 10, v4
	v_lshl_add_u32 v70, v86, 10, v4
	v_lshl_add_u32 v71, v87, 10, v4
	v_lshl_add_u32 v72, v88, 10, v4
	v_lshl_add_u32 v73, v89, 10, v4
	v_lshl_add_u32 v74, v90, 10, v4
	v_lshl_add_u32 v75, v91, 10, v4
	v_lshl_add_u32 v76, v92, 10, v4
	v_lshl_add_u32 v77, v93, 10, v4
	v_lshl_add_u32 v78, v94, 10, v4
	v_lshl_add_u32 v79, v95, 10, v4
	v_lshl_add_u32 v80, v96, 10, v4
	v_lshl_add_u32 v81, v97, 10, v4
	v_lshl_add_u32 v82, v98, 10, v4
	v_lshl_add_u32 v83, v99, 10, v4
	s_add_u32 s18, s60, 0x1100000
	s_addc_u32 s19, s61, 0
	global_load_dwordx4 v[180:183], v4, s[60:61]
	global_load_dwordx4 v[184:187], v4, s[18:19]
	s_add_u32 s14, s58, s20
	s_addc_u32 s15, s59, 0
	global_load_dwordx4 v[84:87], v5, s[14:15] offset:0
	global_load_dwordx4 v[88:91], v5, s[14:15] offset:16
	global_load_dwordx4 v[92:95], v5, s[14:15] offset:32
	global_load_dwordx4 v[96:99], v5, s[14:15] offset:48
	global_load_dwordx4 v[120:123], v68, s[12:13]
	global_load_dwordx4 v[124:127], v69, s[12:13]
	global_load_dwordx4 v[128:131], v70, s[12:13]
	global_load_dwordx4 v[132:135], v71, s[12:13]
	global_load_dwordx4 v[136:139], v72, s[12:13]
	global_load_dwordx4 v[140:143], v73, s[12:13]
	global_load_dwordx4 v[144:147], v74, s[12:13]
	global_load_dwordx4 v[148:151], v75, s[12:13]
	global_load_dwordx4 v[152:155], v76, s[12:13]
	global_load_dwordx4 v[156:159], v77, s[12:13]
	global_load_dwordx4 v[160:163], v78, s[12:13]
	global_load_dwordx4 v[164:167], v79, s[12:13]
	global_load_dwordx4 v[168:171], v80, s[12:13]
	global_load_dwordx4 v[172:175], v81, s[12:13]
	global_load_dwordx4 v[188:191], v82, s[12:13]
	global_load_dwordx4 v[192:195], v83, s[12:13]
	s_mov_b32 s22, 0

;     ...
;     for (int m = 0; m < 16; m += 2) {
;         const u32x4_t a0 = *(const u32x4_t*)(hp + m * 64), a1 = *(const u32x4_t*)(hp + m * 64 + 64);
; #pragma unroll
;         for (int t = 0; t < NTL; ++t) FP8MM(a0, b0[t], acc[t]);
;         if (m + 2 < 16) {
; #pragma unroll
;             for (int t = 0; t < NTL; ++t) b0[t] = *(const u32x4_t*)(up[t] + (m + 2) * 64);
;         }
; #pragma unroll
;         for (int t = 0; t < NTL; ++t) FP8MM(a1, b1[t], acc[t]);
;         if (m + 3 < 16) {
; #pragma unroll
;             for (int t = 0; t < NTL; ++t) b1[t] = *(const u32x4_t*)(up[t] + (m + 3) * 64);
;         }
;     }
.Lg1_nobar:
	s_waitcnt vmcnt(16)
	v_cvt_pk_f32_fp8_e32 v[10:11], v180
	v_cvt_pk_f32_fp8_sdwa v[12:13], v180 src0_sel:WORD_1
	v_cvt_pk_f32_fp8_e32 v[14:15], v181
	v_cvt_pk_f32_fp8_sdwa v[16:17], v181 src0_sel:WORD_1
	v_cvt_pk_f32_fp8_e32 v[18:19], v182
	v_cvt_pk_f32_fp8_sdwa v[20:21], v182 src0_sel:WORD_1
	v_cvt_pk_f32_fp8_e32 v[22:23], v183
	v_cvt_pk_f32_fp8_sdwa v[24:25], v183 src0_sel:WORD_1
	v_cvt_pk_f32_fp8_e32 v[26:27], v184
	v_cvt_pk_f32_fp8_sdwa v[28:29], v184 src0_sel:WORD_1
	v_cvt_pk_f32_fp8_e32 v[30:31], v185
	v_cvt_pk_f32_fp8_sdwa v[32:33], v185 src0_sel:WORD_1
	v_cvt_pk_f32_fp8_e32 v[34:35], v186
	v_cvt_pk_f32_fp8_sdwa v[36:37], v186 src0_sel:WORD_1
	v_cvt_pk_f32_fp8_e32 v[38:39], v187
	v_cvt_pk_f32_fp8_sdwa v[40:41], v187 src0_sel:WORD_1
	v_pk_fma_f32 v[10:11], v[26:27], v[8:9], v[10:11]
	v_pk_fma_f32 v[12:13], v[28:29], v[8:9], v[12:13]
	v_pk_fma_f32 v[14:15], v[30:31], v[8:9], v[14:15]
	v_pk_fma_f32 v[16:17], v[32:33], v[8:9], v[16:17]
	v_pk_fma_f32 v[18:19], v[34:35], v[8:9], v[18:19]
	v_pk_fma_f32 v[20:21], v[36:37], v[8:9], v[20:21]
	v_pk_fma_f32 v[22:23], v[38:39], v[8:9], v[22:23]
	v_pk_fma_f32 v[24:25], v[40:41], v[8:9], v[24:25]
	v_lshl_add_u32 v68, v84, 10, v4
	v_lshl_add_u32 v69, v85, 10, v4
	v_lshl_add_u32 v70, v86, 10, v4
	v_lshl_add_u32 v71, v87, 10, v4
	v_lshl_add_u32 v72, v88, 10, v4
	v_lshl_add_u32 v73, v89, 10, v4
	v_lshl_add_u32 v74, v90, 10, v4
	v_lshl_add_u32 v75, v91, 10, v4
	v_lshl_add_u32 v76, v92, 10, v4
	v_lshl_add_u32 v77, v93, 10, v4
	v_lshl_add_u32 v78, v94, 10, v4
	v_lshl_add_u32 v79, v95, 10, v4
	v_lshl_add_u32 v80, v96, 10, v4
	v_lshl_add_u32 v81, v97, 10, v4
	v_lshl_add_u32 v82, v98, 10, v4
	v_lshl_add_u32 v83, v99, 10, v4
	s_add_u32 s9, s22, 1
	s_and_b32 s10, s9, 7
	s_lshr_b32 s11, s9, 3
	s_mul_i32 s23, s10, s21
	s_lshl_b32 s11, s11, 7
	s_add_u32 s16, s60, s23
	s_addc_u32 s17, s61, 0
	s_add_u32 s16, s16, s11
	s_addc_u32 s17, s17, 0
	s_add_u32 s18, s16, 0x1100000
	s_addc_u32 s19, s17, 0
	s_add_u32 s12, s56, s11
	s_addc_u32 s13, s57, 0
	s_add_u32 s9, s22, 2
	s_and_b32 s9, s9, 7
	s_mul_i32 s9, s9, s20
	s_add_u32 s14, s58, s9
	s_addc_u32 s15, s59, 0
	global_load_dwordx4 v[180:183], v4, s[16:17]
	global_load_dwordx4 v[184:187], v4, s[18:19]
	global_load_dwordx4 v[84:87], v5, s[14:15] offset:0
	global_load_dwordx4 v[88:91], v5, s[14:15] offset:16
	global_load_dwordx4 v[92:95], v5, s[14:15] offset:32
	global_load_dwordx4 v[96:99], v5, s[14:15] offset:48
	s_waitcnt vmcnt(20)
	v_cvt_pk_f32_fp8_e32 v[26:27], v120
	v_cvt_pk_f32_fp8_sdwa v[28:29], v120 src0_sel:WORD_1
	v_cvt_pk_f32_fp8_e32 v[30:31], v121
	v_cvt_pk_f32_fp8_sdwa v[32:33], v121 src0_sel:WORD_1
	v_cvt_pk_f32_fp8_e32 v[34:35], v122
	v_cvt_pk_f32_fp8_sdwa v[36:37], v122 src0_sel:WORD_1
	v_cvt_pk_f32_fp8_e32 v[38:39], v123
	v_cvt_pk_f32_fp8_sdwa v[40:41], v123 src0_sel:WORD_1
	v_cvt_pk_f32_fp8_e32 v[42:43], v124
	v_cvt_pk_f32_fp8_sdwa v[44:45], v124 src0_sel:WORD_1
	v_cvt_pk_f32_fp8_e32 v[46:47], v125
	v_cvt_pk_f32_fp8_sdwa v[48:49], v125 src0_sel:WORD_1
	v_cvt_pk_f32_fp8_e32 v[50:51], v126
	v_cvt_pk_f32_fp8_sdwa v[52:53], v126 src0_sel:WORD_1
	v_cvt_pk_f32_fp8_e32 v[54:55], v127
	v_cvt_pk_f32_fp8_sdwa v[56:57], v127 src0_sel:WORD_1
	global_load_dwordx4 v[120:123], v68, s[12:13]
	global_load_dwordx4 v[124:127], v69, s[12:13]
	v_pk_mul_f32 v[58:59], v[26:27], v[10:11]
	v_pk_mul_f32 v[60:61], v[42:43], v[10:11]
	v_pk_fma_f32 v[58:59], v[28:29], v[12:13], v[58:59]
	v_pk_fma_f32 v[60:61], v[44:45], v[12:13], v[60:61]
	v_pk_fma_f32 v[58:59], v[30:31], v[14:15], v[58:59]
	v_pk_fma_f32 v[60:61], v[46:47], v[14:15], v[60:61]
	v_pk_fma_f32 v[58:59], v[32:33], v[16:17], v[58:59]
	v_pk_fma_f32 v[60:61], v[48:49], v[16:17], v[60:61]
	v_pk_fma_f32 v[58:59], v[34:35], v[18:19], v[58:59]
	v_pk_fma_f32 v[60:61], v[50:51], v[18:19], v[60:61]
	v_pk_fma_f32 v[58:59], v[36:37], v[20:21], v[58:59]
	v_pk_fma_f32 v[60:61], v[52:53], v[20:21], v[60:61]
	v_pk_fma_f32 v[58:59], v[38:39], v[22:23], v[58:59]
	v_pk_fma_f32 v[60:61], v[54:55], v[22:23], v[60:61]
	v_pk_fma_f32 v[58:59], v[40:41], v[24:25], v[58:59]
	v_pk_fma_f32 v[60:61], v[56:57], v[24:25], v[60:61]
	v_add_f32_e32 v104, v58, v59
	v_add_f32_e32 v105, v60, v61
	s_waitcnt vmcnt(20)
	v_cvt_pk_f32_fp8_e32 v[26:27], v128
	v_cvt_pk_f32_fp8_sdwa v[28:29], v128 src0_sel:WORD_1
	v_cvt_pk_f32_fp8_e32 v[30:31], v129
	v_cvt_pk_f32_fp8_sdwa v[32:33], v129 src0_sel:WORD_1
	v_cvt_pk_f32_fp8_e32 v[34:35], v130
	v_cvt_pk_f32_fp8_sdwa v[36:37], v130 src0_sel:WORD_1
	v_cvt_pk_f32_fp8_e32 v[38:39], v131
	v_cvt_pk_f32_fp8_sdwa v[40:41], v131 src0_sel:WORD_1
	v_cvt_pk_f32_fp8_e32 v[42:43], v132
	v_cvt_pk_f32_fp8_sdwa v[44:45], v132 src0_sel:WORD_1
	v_cvt_pk_f32_fp8_e32 v[46:47], v133
	v_cvt_pk_f32_fp8_sdwa v[48:49], v133 src0_sel:WORD_1
	v_cvt_pk_f32_fp8_e32 v[50:51], v134
	v_cvt_pk_f32_fp8_sdwa v[52:53], v134 src0_sel:WORD_1
	v_cvt_pk_f32_fp8_e32 v[54:55], v135
	v_cvt_pk_f32_fp8_sdwa v[56:57], v135 src0_sel:WORD_1
	global_load_dwordx4 v[128:131], v70, s[12:13]
	global_load_dwordx4 v[132:135], v71, s[12:13]
	v_pk_mul_f32 v[58:59], v[26:27], v[10:11]
	v_pk_mul_f32 v[60:61], v[42:43], v[10:11]
	v_pk_fma_f32 v[58:59], v[28:29], v[12:13], v[58:59]
	v_pk_fma_f32 v[60:61], v[44:45], v[12:13], v[60:61]
	v_pk_fma_f32 v[58:59], v[30:31], v[14:15], v[58:59]
	v_pk_fma_f32 v[60:61], v[46:47], v[14:15], v[60:61]
	v_pk_fma_f32 v[58:59], v[32:33], v[16:17], v[58:59]
	v_pk_fma_f32 v[60:61], v[48:49], v[16:17], v[60:61]
	v_pk_fma_f32 v[58:59], v[34:35], v[18:19], v[58:59]
	v_pk_fma_f32 v[60:61], v[50:51], v[18:19], v[60:61]
	v_pk_fma_f32 v[58:59], v[36:37], v[20:21], v[58:59]
	v_pk_fma_f32 v[60:61], v[52:53], v[20:21], v[60:61]
	v_pk_fma_f32 v[58:59], v[38:39], v[22:23], v[58:59]
	v_pk_fma_f32 v[60:61], v[54:55], v[22:23], v[60:61]
	v_pk_fma_f32 v[58:59], v[40:41], v[24:25], v[58:59]
	v_pk_fma_f32 v[60:61], v[56:57], v[24:25], v[60:61]
	v_add_f32_e32 v106, v58, v59
	v_add_f32_e32 v107, v60, v61
	s_waitcnt vmcnt(20)
;     ...
;     for (int m = 0; m < 16; m += 2) {
;         const u32x4_t a0 = *(const u32x4_t*)(hp + m * 64), a1 = *(const u32x4_t*)(hp + m * 64 + 64);
; #pragma unroll
;         for (int t = 0; t < NTL; ++t) FP8MM(a0, b0[t], acc[t]);
;         if (m + 2 < 16) {
; #pragma unroll
;             for (int t = 0; t < NTL; ++t) b0[t] = *(const u32x4_t*)(up[t] + (m + 2) * 64);
;         }
; #pragma unroll
;         for (int t = 0; t < NTL; ++t) FP8MM(a1, b1[t], acc[t]);
;         if (m + 3 < 16) {
; #pragma unroll
;             for (int t = 0; t < NTL; ++t) b1[t] = *(const u32x4_t*)(up[t] + (m + 3) * 64);
;         }
;     }
	v_cvt_pk_f32_fp8_e32 v[26:27], v136
	v_cvt_pk_f32_fp8_sdwa v[28:29], v136 src0_sel:WORD_1
	v_cvt_pk_f32_fp8_e32 v[30:31], v137
	v_cvt_pk_f32_fp8_sdwa v[32:33], v137 src0_sel:WORD_1
	v_cvt_pk_f32_fp8_e32 v[34:35], v138
	v_cvt_pk_f32_fp8_sdwa v[36:37], v138 src0_sel:WORD_1
	v_cvt_pk_f32_fp8_e32 v[38:39], v139
	v_cvt_pk_f32_fp8_sdwa v[40:41], v139 src0_sel:WORD_1
	v_cvt_pk_f32_fp8_e32 v[42:43], v140
	v_cvt_pk_f32_fp8_sdwa v[44:45], v140 src0_sel:WORD_1
	v_cvt_pk_f32_fp8_e32 v[46:47], v141
	v_cvt_pk_f32_fp8_sdwa v[48:49], v141 src0_sel:WORD_1
	v_cvt_pk_f32_fp8_e32 v[50:51], v142
	v_cvt_pk_f32_fp8_sdwa v[52:53], v142 src0_sel:WORD_1
	v_cvt_pk_f32_fp8_e32 v[54:55], v143
	v_cvt_pk_f32_fp8_sdwa v[56:57], v143 src0_sel:WORD_1
	global_load_dwordx4 v[136:139], v72, s[12:13]
	global_load_dwordx4 v[140:143], v73, s[12:13]
	v_pk_mul_f32 v[58:59], v[26:27], v[10:11]
	v_pk_mul_f32 v[60:61], v[42:43], v[10:11]
	v_pk_fma_f32 v[58:59], v[28:29], v[12:13], v[58:59]
	v_pk_fma_f32 v[60:61], v[44:45], v[12:13], v[60:61]
	v_pk_fma_f32 v[58:59], v[30:31], v[14:15], v[58:59]
	v_pk_fma_f32 v[60:61], v[46:47], v[14:15], v[60:61]
	v_pk_fma_f32 v[58:59], v[32:33], v[16:17], v[58:59]
	v_pk_fma_f32 v[60:61], v[48:49], v[16:17], v[60:61]
	v_pk_fma_f32 v[58:59], v[34:35], v[18:19], v[58:59]
	v_pk_fma_f32 v[60:61], v[50:51], v[18:19], v[60:61]
	v_pk_fma_f32 v[58:59], v[36:37], v[20:21], v[58:59]
	v_pk_fma_f32 v[60:61], v[52:53], v[20:21], v[60:61]
	v_pk_fma_f32 v[58:59], v[38:39], v[22:23], v[58:59]
	v_pk_fma_f32 v[60:61], v[54:55], v[22:23], v[60:61]
	v_pk_fma_f32 v[58:59], v[40:41], v[24:25], v[58:59]
	v_pk_fma_f32 v[60:61], v[56:57], v[24:25], v[60:61]
	v_add_f32_e32 v108, v58, v59
	v_add_f32_e32 v109, v60, v61
	s_waitcnt vmcnt(20)
	v_cvt_pk_f32_fp8_e32 v[26:27], v144
	v_cvt_pk_f32_fp8_sdwa v[28:29], v144 src0_sel:WORD_1
	v_cvt_pk_f32_fp8_e32 v[30:31], v145
	v_cvt_pk_f32_fp8_sdwa v[32:33], v145 src0_sel:WORD_1
	v_cvt_pk_f32_fp8_e32 v[34:35], v146
	v_cvt_pk_f32_fp8_sdwa v[36:37], v146 src0_sel:WORD_1
	v_cvt_pk_f32_fp8_e32 v[38:39], v147
	v_cvt_pk_f32_fp8_sdwa v[40:41], v147 src0_sel:WORD_1
	v_cvt_pk_f32_fp8_e32 v[42:43], v148
	v_cvt_pk_f32_fp8_sdwa v[44:45], v148 src0_sel:WORD_1
	v_cvt_pk_f32_fp8_e32 v[46:47], v149
	v_cvt_pk_f32_fp8_sdwa v[48:49], v149 src0_sel:WORD_1
	v_cvt_pk_f32_fp8_e32 v[50:51], v150
	v_cvt_pk_f32_fp8_sdwa v[52:53], v150 src0_sel:WORD_1
	v_cvt_pk_f32_fp8_e32 v[54:55], v151
	v_cvt_pk_f32_fp8_sdwa v[56:57], v151 src0_sel:WORD_1
	global_load_dwordx4 v[144:147], v74, s[12:13]
	global_load_dwordx4 v[148:151], v75, s[12:13]
	v_pk_mul_f32 v[58:59], v[26:27], v[10:11]
	v_pk_mul_f32 v[60:61], v[42:43], v[10:11]
	v_pk_fma_f32 v[58:59], v[28:29], v[12:13], v[58:59]
	v_pk_fma_f32 v[60:61], v[44:45], v[12:13], v[60:61]
	v_pk_fma_f32 v[58:59], v[30:31], v[14:15], v[58:59]
	v_pk_fma_f32 v[60:61], v[46:47], v[14:15], v[60:61]
	v_pk_fma_f32 v[58:59], v[32:33], v[16:17], v[58:59]
	v_pk_fma_f32 v[60:61], v[48:49], v[16:17], v[60:61]
	v_pk_fma_f32 v[58:59], v[34:35], v[18:19], v[58:59]
	v_pk_fma_f32 v[60:61], v[50:51], v[18:19], v[60:61]
	v_pk_fma_f32 v[58:59], v[36:37], v[20:21], v[58:59]
	v_pk_fma_f32 v[60:61], v[52:53], v[20:21], v[60:61]
	v_pk_fma_f32 v[58:59], v[38:39], v[22:23], v[58:59]
	v_pk_fma_f32 v[60:61], v[54:55], v[22:23], v[60:61]
	v_pk_fma_f32 v[58:59], v[40:41], v[24:25], v[58:59]
	v_pk_fma_f32 v[60:61], v[56:57], v[24:25], v[60:61]
	v_add_f32_e32 v110, v58, v59
	v_add_f32_e32 v111, v60, v61
	s_waitcnt vmcnt(20)
	v_cvt_pk_f32_fp8_e32 v[26:27], v152
	v_cvt_pk_f32_fp8_sdwa v[28:29], v152 src0_sel:WORD_1
	v_cvt_pk_f32_fp8_e32 v[30:31], v153
	v_cvt_pk_f32_fp8_sdwa v[32:33], v153 src0_sel:WORD_1
	v_cvt_pk_f32_fp8_e32 v[34:35], v154
	v_cvt_pk_f32_fp8_sdwa v[36:37], v154 src0_sel:WORD_1
	v_cvt_pk_f32_fp8_e32 v[38:39], v155
	v_cvt_pk_f32_fp8_sdwa v[40:41], v155 src0_sel:WORD_1
	v_cvt_pk_f32_fp8_e32 v[42:43], v156
	v_cvt_pk_f32_fp8_sdwa v[44:45], v156 src0_sel:WORD_1
	v_cvt_pk_f32_fp8_e32 v[46:47], v157
	v_cvt_pk_f32_fp8_sdwa v[48:49], v157 src0_sel:WORD_1
	v_cvt_pk_f32_fp8_e32 v[50:51], v158
	v_cvt_pk_f32_fp8_sdwa v[52:53], v158 src0_sel:WORD_1
	v_cvt_pk_f32_fp8_e32 v[54:55], v159
	v_cvt_pk_f32_fp8_sdwa v[56:57], v159 src0_sel:WORD_1
	global_load_dwordx4 v[152:155], v76, s[12:13]
	global_load_dwordx4 v[156:159], v77, s[12:13]
	v_pk_mul_f32 v[58:59], v[26:27], v[10:11]
	v_pk_mul_f32 v[60:61], v[42:43], v[10:11]
	v_pk_fma_f32 v[58:59], v[28:29], v[12:13], v[58:59]
	v_pk_fma_f32 v[60:61], v[44:45], v[12:13], v[60:61]
	v_pk_fma_f32 v[58:59], v[30:31], v[14:15], v[58:59]
	v_pk_fma_f32 v[60:61], v[46:47], v[14:15], v[60:61]
	v_pk_fma_f32 v[58:59], v[32:33], v[16:17], v[58:59]
	v_pk_fma_f32 v[60:61], v[48:49], v[16:17], v[60:61]
	v_pk_fma_f32 v[58:59], v[34:35], v[18:19], v[58:59]
	v_pk_fma_f32 v[60:61], v[50:51], v[18:19], v[60:61]
	v_pk_fma_f32 v[58:59], v[36:37], v[20:21], v[58:59]
	v_pk_fma_f32 v[60:61], v[52:53], v[20:21], v[60:61]
	v_pk_fma_f32 v[58:59], v[38:39], v[22:23], v[58:59]
	v_pk_fma_f32 v[60:61], v[54:55], v[22:23], v[60:61]
	v_pk_fma_f32 v[58:59], v[40:41], v[24:25], v[58:59]
	v_pk_fma_f32 v[60:61], v[56:57], v[24:25], v[60:61]
	v_add_f32_e32 v112, v58, v59
	v_add_f32_e32 v113, v60, v61
	s_waitcnt vmcnt(20)
;     ...
;     for (int m = 0; m < 16; m += 2) {
;         const u32x4_t a0 = *(const u32x4_t*)(hp + m * 64), a1 = *(const u32x4_t*)(hp + m * 64 + 64);
; #pragma unroll
;         for (int t = 0; t < NTL; ++t) FP8MM(a0, b0[t], acc[t]);
;         if (m + 2 < 16) {
; #pragma unroll
;             for (int t = 0; t < NTL; ++t) b0[t] = *(const u32x4_t*)(up[t] + (m + 2) * 64);
;         }
; #pragma unroll
;         for (int t = 0; t < NTL; ++t) FP8MM(a1, b1[t], acc[t]);
;         if (m + 3 < 16) {
; #pragma unroll
;             for (int t = 0; t < NTL; ++t) b1[t] = *(const u32x4_t*)(up[t] + (m + 3) * 64);
;         }
;     }
;     ...
; #pragma unroll
;     for (int t = 0; t < NTL; ++t) { const float lo = __shfl_xor(acc[t][0], 32); const float dot = (acc[t][0] + lo * (1.f / 32.f)) * s_u[t];
	v_cvt_pk_f32_fp8_e32 v[26:27], v160
	v_cvt_pk_f32_fp8_sdwa v[28:29], v160 src0_sel:WORD_1
	v_cvt_pk_f32_fp8_e32 v[30:31], v161
	v_cvt_pk_f32_fp8_sdwa v[32:33], v161 src0_sel:WORD_1
	v_cvt_pk_f32_fp8_e32 v[34:35], v162
	v_cvt_pk_f32_fp8_sdwa v[36:37], v162 src0_sel:WORD_1
	v_cvt_pk_f32_fp8_e32 v[38:39], v163
	v_cvt_pk_f32_fp8_sdwa v[40:41], v163 src0_sel:WORD_1
	v_cvt_pk_f32_fp8_e32 v[42:43], v164
	v_cvt_pk_f32_fp8_sdwa v[44:45], v164 src0_sel:WORD_1
	v_cvt_pk_f32_fp8_e32 v[46:47], v165
	v_cvt_pk_f32_fp8_sdwa v[48:49], v165 src0_sel:WORD_1
	v_cvt_pk_f32_fp8_e32 v[50:51], v166
	v_cvt_pk_f32_fp8_sdwa v[52:53], v166 src0_sel:WORD_1
	v_cvt_pk_f32_fp8_e32 v[54:55], v167
	v_cvt_pk_f32_fp8_sdwa v[56:57], v167 src0_sel:WORD_1
	global_load_dwordx4 v[160:163], v78, s[12:13]
	global_load_dwordx4 v[164:167], v79, s[12:13]
	v_pk_mul_f32 v[58:59], v[26:27], v[10:11]
	v_pk_mul_f32 v[60:61], v[42:43], v[10:11]
	v_pk_fma_f32 v[58:59], v[28:29], v[12:13], v[58:59]
	v_pk_fma_f32 v[60:61], v[44:45], v[12:13], v[60:61]
	v_pk_fma_f32 v[58:59], v[30:31], v[14:15], v[58:59]
	v_pk_fma_f32 v[60:61], v[46:47], v[14:15], v[60:61]
	v_pk_fma_f32 v[58:59], v[32:33], v[16:17], v[58:59]
	v_pk_fma_f32 v[60:61], v[48:49], v[16:17], v[60:61]
	v_pk_fma_f32 v[58:59], v[34:35], v[18:19], v[58:59]
	v_pk_fma_f32 v[60:61], v[50:51], v[18:19], v[60:61]
	v_pk_fma_f32 v[58:59], v[36:37], v[20:21], v[58:59]
	v_pk_fma_f32 v[60:61], v[52:53], v[20:21], v[60:61]
	v_pk_fma_f32 v[58:59], v[38:39], v[22:23], v[58:59]
	v_pk_fma_f32 v[60:61], v[54:55], v[22:23], v[60:61]
	v_pk_fma_f32 v[58:59], v[40:41], v[24:25], v[58:59]
	v_pk_fma_f32 v[60:61], v[56:57], v[24:25], v[60:61]
	v_add_f32_e32 v114, v58, v59
	v_add_f32_e32 v115, v60, v61
	s_waitcnt vmcnt(20)
	v_cvt_pk_f32_fp8_e32 v[26:27], v168
	v_cvt_pk_f32_fp8_sdwa v[28:29], v168 src0_sel:WORD_1
	v_cvt_pk_f32_fp8_e32 v[30:31], v169
	v_cvt_pk_f32_fp8_sdwa v[32:33], v169 src0_sel:WORD_1
	v_cvt_pk_f32_fp8_e32 v[34:35], v170
	v_cvt_pk_f32_fp8_sdwa v[36:37], v170 src0_sel:WORD_1
	v_cvt_pk_f32_fp8_e32 v[38:39], v171
	v_cvt_pk_f32_fp8_sdwa v[40:41], v171 src0_sel:WORD_1
	v_cvt_pk_f32_fp8_e32 v[42:43], v172
	v_cvt_pk_f32_fp8_sdwa v[44:45], v172 src0_sel:WORD_1
	v_cvt_pk_f32_fp8_e32 v[46:47], v173
	v_cvt_pk_f32_fp8_sdwa v[48:49], v173 src0_sel:WORD_1
	v_cvt_pk_f32_fp8_e32 v[50:51], v174
	v_cvt_pk_f32_fp8_sdwa v[52:53], v174 src0_sel:WORD_1
	v_cvt_pk_f32_fp8_e32 v[54:55], v175
	v_cvt_pk_f32_fp8_sdwa v[56:57], v175 src0_sel:WORD_1
	global_load_dwordx4 v[168:171], v80, s[12:13]
	global_load_dwordx4 v[172:175], v81, s[12:13]
	v_pk_mul_f32 v[58:59], v[26:27], v[10:11]
	v_pk_mul_f32 v[60:61], v[42:43], v[10:11]
	v_pk_fma_f32 v[58:59], v[28:29], v[12:13], v[58:59]
	v_pk_fma_f32 v[60:61], v[44:45], v[12:13], v[60:61]
	v_pk_fma_f32 v[58:59], v[30:31], v[14:15], v[58:59]
	v_pk_fma_f32 v[60:61], v[46:47], v[14:15], v[60:61]
	v_pk_fma_f32 v[58:59], v[32:33], v[16:17], v[58:59]
	v_pk_fma_f32 v[60:61], v[48:49], v[16:17], v[60:61]
	v_pk_fma_f32 v[58:59], v[34:35], v[18:19], v[58:59]
	v_pk_fma_f32 v[60:61], v[50:51], v[18:19], v[60:61]
	v_pk_fma_f32 v[58:59], v[36:37], v[20:21], v[58:59]
	v_pk_fma_f32 v[60:61], v[52:53], v[20:21], v[60:61]
	v_pk_fma_f32 v[58:59], v[38:39], v[22:23], v[58:59]
	v_pk_fma_f32 v[60:61], v[54:55], v[22:23], v[60:61]
	v_pk_fma_f32 v[58:59], v[40:41], v[24:25], v[58:59]
	v_pk_fma_f32 v[60:61], v[56:57], v[24:25], v[60:61]
	v_add_f32_e32 v62, v58, v59
	v_add_f32_e32 v63, v60, v61
	s_waitcnt vmcnt(20)
	v_cvt_pk_f32_fp8_e32 v[26:27], v188
	v_cvt_pk_f32_fp8_sdwa v[28:29], v188 src0_sel:WORD_1
	v_cvt_pk_f32_fp8_e32 v[30:31], v189
	v_cvt_pk_f32_fp8_sdwa v[32:33], v189 src0_sel:WORD_1
	v_cvt_pk_f32_fp8_e32 v[34:35], v190
	v_cvt_pk_f32_fp8_sdwa v[36:37], v190 src0_sel:WORD_1
	v_cvt_pk_f32_fp8_e32 v[38:39], v191
	v_cvt_pk_f32_fp8_sdwa v[40:41], v191 src0_sel:WORD_1
	v_cvt_pk_f32_fp8_e32 v[42:43], v192
	v_cvt_pk_f32_fp8_sdwa v[44:45], v192 src0_sel:WORD_1
	v_cvt_pk_f32_fp8_e32 v[46:47], v193
	v_cvt_pk_f32_fp8_sdwa v[48:49], v193 src0_sel:WORD_1
	v_cvt_pk_f32_fp8_e32 v[50:51], v194
	v_cvt_pk_f32_fp8_sdwa v[52:53], v194 src0_sel:WORD_1
	v_cvt_pk_f32_fp8_e32 v[54:55], v195
	v_cvt_pk_f32_fp8_sdwa v[56:57], v195 src0_sel:WORD_1
	global_load_dwordx4 v[188:191], v82, s[12:13]
	global_load_dwordx4 v[192:195], v83, s[12:13]
	v_pk_mul_f32 v[58:59], v[26:27], v[10:11]
	v_pk_mul_f32 v[60:61], v[42:43], v[10:11]
	v_pk_fma_f32 v[58:59], v[28:29], v[12:13], v[58:59]
	v_pk_fma_f32 v[60:61], v[44:45], v[12:13], v[60:61]
	v_pk_fma_f32 v[58:59], v[30:31], v[14:15], v[58:59]
	v_pk_fma_f32 v[60:61], v[46:47], v[14:15], v[60:61]
	v_pk_fma_f32 v[58:59], v[32:33], v[16:17], v[58:59]
	v_pk_fma_f32 v[60:61], v[48:49], v[16:17], v[60:61]
	v_pk_fma_f32 v[58:59], v[34:35], v[18:19], v[58:59]
	v_pk_fma_f32 v[60:61], v[50:51], v[18:19], v[60:61]
	v_pk_fma_f32 v[58:59], v[36:37], v[20:21], v[58:59]
	v_pk_fma_f32 v[60:61], v[52:53], v[20:21], v[60:61]
	v_pk_fma_f32 v[58:59], v[38:39], v[22:23], v[58:59]
	v_pk_fma_f32 v[60:61], v[54:55], v[22:23], v[60:61]
	v_pk_fma_f32 v[58:59], v[40:41], v[24:25], v[58:59]
	v_pk_fma_f32 v[60:61], v[56:57], v[24:25], v[60:61]
	v_add_f32_e32 v64, v58, v59
	v_add_f32_e32 v65, v60, v61
	s_nop 1
	v_add_f32_dpp v104, v104, v104 row_half_mirror row_mask:0xf bank_mask:0x5
	v_add_f32_dpp v104, v112, v112 row_half_mirror row_mask:0xf bank_mask:0xa
	v_add_f32_dpp v105, v105, v105 row_half_mirror row_mask:0xf bank_mask:0x5
	v_add_f32_dpp v105, v113, v113 row_half_mirror row_mask:0xf bank_mask:0xa
	v_add_f32_dpp v106, v106, v106 row_half_mirror row_mask:0xf bank_mask:0x5
	v_add_f32_dpp v106, v114, v114 row_half_mirror row_mask:0xf bank_mask:0xa
;     DEVI int* eidx() const { return (int*)(ws + WS_EIDX); }
; DEVI float gelu_f(float x) { const float u = 0.7978845608028654f * (x + 0.044715f * x * x * x); return x * __builtin_amdgcn_rcpf(1.f + __expf(-2.f * u)); }
;     ...
;     for (int t = 0; t < NTL; ++t) { e[t] = eidx[(size_t)r * 128 + (tbase + t) * 16 + n16]; g[t] = gwv[(size_t)r * 128 + (tbase + t) * 16 + n16]; }
; #pragma unroll
;     for (int t = 0; t < NTL; ++t) { s_u[t] = su[e[t]]; s_v[t] = sv[e[t]]; }
;     ...
;     for (int m = 0; m < 16; m += 2) {
;         const u32x4_t a0 = *(const u32x4_t*)(hp + m * 64), a1 = *(const u32x4_t*)(hp + m * 64 + 64);
; #pragma unroll
;         for (int t = 0; t < NTL; ++t) FP8MM(a0, b0[t], acc[t]);
;         if (m + 2 < 16) {
; #pragma unroll
;             for (int t = 0; t < NTL; ++t) b0[t] = *(const u32x4_t*)(up[t] + (m + 2) * 64);
;         }
; #pragma unroll
;         for (int t = 0; t < NTL; ++t) FP8MM(a1, b1[t], acc[t]);
;         if (m + 3 < 16) {
; #pragma unroll
;             for (int t = 0; t < NTL; ++t) b1[t] = *(const u32x4_t*)(up[t] + (m + 3) * 64);
;         }
;     }
;     ...
; #pragma unroll
;     for (int t = 0; t < NTL; ++t) { const float lo = __shfl_xor(acc[t][0], 32); const float dot = (acc[t][0] + lo * (1.f / 32.f)) * s_u[t];
;         if (kq == 0) pl[t * 16 + n16] = (u32x2_t){(unsigned)e[t], __float_as_uint(g[t] * gelu_f(dot) * s_v[t])}; }
	v_add_f32_dpp v107, v107, v107 row_half_mirror row_mask:0xf bank_mask:0x5
	v_add_f32_dpp v107, v115, v115 row_half_mirror row_mask:0xf bank_mask:0xa
	v_add_f32_dpp v108, v108, v108 row_half_mirror row_mask:0xf bank_mask:0x5
	v_add_f32_dpp v108, v62, v62 row_half_mirror row_mask:0xf bank_mask:0xa
	v_add_f32_dpp v109, v109, v109 row_half_mirror row_mask:0xf bank_mask:0x5
	v_add_f32_dpp v109, v63, v63 row_half_mirror row_mask:0xf bank_mask:0xa
	v_add_f32_dpp v110, v110, v110 row_half_mirror row_mask:0xf bank_mask:0x5
	v_add_f32_dpp v110, v64, v64 row_half_mirror row_mask:0xf bank_mask:0xa
	v_add_f32_dpp v111, v111, v111 row_half_mirror row_mask:0xf bank_mask:0x5
	v_add_f32_dpp v111, v65, v65 row_half_mirror row_mask:0xf bank_mask:0xa
	v_cndmask_b32_e64 v26, v104, v106, s[40:41]
	v_cndmask_b32_e64 v27, v106, v104, s[40:41]
	v_cndmask_b32_e64 v28, v105, v107, s[40:41]
	v_cndmask_b32_e64 v29, v107, v105, s[40:41]
	v_cndmask_b32_e64 v30, v108, v110, s[40:41]
	v_cndmask_b32_e64 v31, v110, v108, s[40:41]
	v_cndmask_b32_e64 v32, v109, v111, s[40:41]
	v_cndmask_b32_e64 v33, v111, v109, s[40:41]
	v_add_f32_dpp v104, v27, v26 quad_perm:[1,0,3,2] row_mask:0xf bank_mask:0xf
	v_add_f32_dpp v105, v29, v28 quad_perm:[1,0,3,2] row_mask:0xf bank_mask:0xf
	v_add_f32_dpp v108, v31, v30 quad_perm:[1,0,3,2] row_mask:0xf bank_mask:0xf
	v_add_f32_dpp v109, v33, v32 quad_perm:[1,0,3,2] row_mask:0xf bank_mask:0xf
	v_cndmask_b32_e64 v26, v104, v108, s[42:43]
	v_cndmask_b32_e64 v27, v108, v104, s[42:43]
	v_cndmask_b32_e64 v28, v105, v109, s[42:43]
	v_cndmask_b32_e64 v29, v109, v105, s[42:43]
	s_nop 0
	v_add_f32_dpp v118, v27, v26 quad_perm:[2,3,0,1] row_mask:0xf bank_mask:0xf
	v_add_f32_dpp v119, v29, v28 quad_perm:[2,3,0,1] row_mask:0xf bank_mask:0xf
	s_and_b32 s9, s22, 7
	s_lshl_b32 s9, s9, 10
	v_add_u32_e32 v7, s9, v6
	ds_add_f32 v7, v118 offset:4
	ds_add_f32 v7, v119 offset:12
	s_add_u32 s22, s22, 1
	s_cmp_lg_u32 s22, 64
	s_cbranch_scc1 .Lg1_loop
	s_waitcnt vmcnt(0) lgkmcnt(0)
	s_lshl_b32 s9, s48, 9
	s_lshl_b32 s20, s34, 9
	s_add_u32 s10, s6, 0x1b292100
	s_addc_u32 s11, s7, 0
	s_add_u32 s10, s10, s9
	s_addc_u32 s11, s11, 0
	s_add_u32 s12, s6, 0x1bb12100
	s_addc_u32 s13, s7, 0
	s_add_u32 s12, s12, s9
	s_addc_u32 s13, s13, 0
	s_lshl_b32 s9, s8, 16
	s_add_u32 s16, s6, 0x2fa42100
	s_addc_u32 s17, s7, 0
	s_add_u32 s16, s16, s9
	s_addc_u32 s17, s17, 0
	s_add_u32 s18, s16, 0x40000
	s_addc_u32 s19, s17, 0
	v_lshlrev_b32_e32 v2, 3, v1
	v_lshl_add_u32 v3, v1, 4, s85
	ds_read_b128 v[68:71], v3 offset:0
	ds_read_b128 v[72:75], v3 offset:1024
	ds_read_b128 v[76:79], v3 offset:2048
	ds_read_b128 v[80:83], v3 offset:3072
	ds_read_b128 v[84:87], v3 offset:4096
	ds_read_b128 v[88:91], v3 offset:5120
	ds_read_b128 v[92:95], v3 offset:6144
	ds_read_b128 v[96:99], v3 offset:7168
	global_load_dwordx2 v[20:21], v2, s[10:11]
	global_load_dwordx2 v[22:23], v2, s[12:13]
	s_add_u32 s10, s10, s20
	s_addc_u32 s11, s11, 0
	s_add_u32 s12, s12, s20
	s_addc_u32 s13, s13, 0
	global_load_dwordx2 v[24:25], v2, s[10:11]
	global_load_dwordx2 v[26:27], v2, s[12:13]
	s_add_u32 s10, s10, s20
	s_addc_u32 s11, s11, 0
	s_add_u32 s12, s12, s20
	s_addc_u32 s13, s13, 0
	global_load_dwordx2 v[28:29], v2, s[10:11]
	global_load_dwordx2 v[30:31], v2, s[12:13]
	s_add_u32 s10, s10, s20
	s_addc_u32 s11, s11, 0
	s_add_u32 s12, s12, s20
	s_addc_u32 s13, s13, 0
	global_load_dwordx2 v[32:33], v2, s[10:11]
	global_load_dwordx2 v[34:35], v2, s[12:13]
	s_add_u32 s10, s10, s20
	s_addc_u32 s11, s11, 0
	s_add_u32 s12, s12, s20
	s_addc_u32 s13, s13, 0
	global_load_dwordx2 v[36:37], v2, s[10:11]
	global_load_dwordx2 v[38:39], v2, s[12:13]
	s_add_u32 s10, s10, s20
	s_addc_u32 s11, s11, 0
	s_add_u32 s12, s12, s20
	s_addc_u32 s13, s13, 0
	global_load_dwordx2 v[40:41], v2, s[10:11]
	global_load_dwordx2 v[42:43], v2, s[12:13]
	s_add_u32 s10, s10, s20
	s_addc_u32 s11, s11, 0
	s_add_u32 s12, s12, s20
	s_addc_u32 s13, s13, 0
	global_load_dwordx2 v[44:45], v2, s[10:11]
	global_load_dwordx2 v[46:47], v2, s[12:13]
	s_add_u32 s10, s10, s20
	s_addc_u32 s11, s11, 0
	s_add_u32 s12, s12, s20
	s_addc_u32 s13, s13, 0
	global_load_dwordx2 v[48:49], v2, s[10:11]
	global_load_dwordx2 v[50:51], v2, s[12:13]
	s_add_u32 s10, s10, s20
	s_addc_u32 s11, s11, 0
	s_add_u32 s12, s12, s20
	s_addc_u32 s13, s13, 0
	s_waitcnt vmcnt(15)
	v_lshlrev_b32_e32 v4, 2, v20
	v_lshlrev_b32_e32 v5, 2, v21
	global_load_dword v120, v4, s[16:17]
	global_load_dword v121, v5, s[16:17]
	global_load_dword v122, v4, s[18:19]
	global_load_dword v123, v5, s[18:19]
	s_waitcnt vmcnt(17)
	v_lshlrev_b32_e32 v4, 2, v24
	v_lshlrev_b32_e32 v5, 2, v25
	global_load_dword v124, v4, s[16:17]
	global_load_dword v125, v5, s[16:17]
	global_load_dword v126, v4, s[18:19]
	global_load_dword v127, v5, s[18:19]
	s_waitcnt vmcnt(19)
	v_lshlrev_b32_e32 v4, 2, v28
	v_lshlrev_b32_e32 v5, 2, v29
	global_load_dword v128, v4, s[16:17]
	global_load_dword v129, v5, s[16:17]
	global_load_dword v130, v4, s[18:19]
	global_load_dword v131, v5, s[18:19]
	s_waitcnt vmcnt(21)
	v_lshlrev_b32_e32 v4, 2, v32
	v_lshlrev_b32_e32 v5, 2, v33
	global_load_dword v132, v4, s[16:17]
	global_load_dword v133, v5, s[16:17]
	global_load_dword v134, v4, s[18:19]
	global_load_dword v135, v5, s[18:19]
	s_waitcnt vmcnt(23)
	v_lshlrev_b32_e32 v4, 2, v36
	v_lshlrev_b32_e32 v5, 2, v37
	global_load_dword v136, v4, s[16:17]
	global_load_dword v137, v5, s[16:17]
	global_load_dword v138, v4, s[18:19]
	global_load_dword v139, v5, s[18:19]
	s_waitcnt vmcnt(25)
	v_lshlrev_b32_e32 v4, 2, v40
	v_lshlrev_b32_e32 v5, 2, v41
	global_load_dword v140, v4, s[16:17]
	global_load_dword v141, v5, s[16:17]
	global_load_dword v142, v4, s[18:19]
	global_load_dword v143, v5, s[18:19]
	s_waitcnt vmcnt(27)
; DEVI float gelu_f(float x) { const float u = 0.7978845608028654f * (x + 0.044715f * x * x * x); return x * __builtin_amdgcn_rcpf(1.f + __expf(-2.f * u)); }
;     ...
;     for (int t = 0; t < NTL; ++t) { const float lo = __shfl_xor(acc[t][0], 32); const float dot = (acc[t][0] + lo * (1.f / 32.f)) * s_u[t];
;         if (kq == 0) pl[t * 16 + n16] = (u32x2_t){(unsigned)e[t], __float_as_uint(g[t] * gelu_f(dot) * s_v[t])}; }
	v_lshlrev_b32_e32 v4, 2, v44
	v_lshlrev_b32_e32 v5, 2, v45
	global_load_dword v144, v4, s[16:17]
	global_load_dword v145, v5, s[16:17]
	global_load_dword v146, v4, s[18:19]
	global_load_dword v147, v5, s[18:19]
	s_waitcnt vmcnt(29)
	v_lshlrev_b32_e32 v4, 2, v48
	v_lshlrev_b32_e32 v5, 2, v49
	global_load_dword v148, v4, s[16:17]
	global_load_dword v149, v5, s[16:17]
	global_load_dword v150, v4, s[18:19]
	global_load_dword v151, v5, s[18:19]
	s_waitcnt lgkmcnt(0)
	s_waitcnt vmcnt(28)
	v_mul_f32_e32 v69, v69, v120
	v_mul_f32_e32 v6, 0x3d372713, v69
	v_mul_f32_e32 v6, v69, v6
	v_fma_f32 v6, v69, v6, v69
	v_mul_f32_e32 v6, 0x3f4c422a, v6
	v_mul_f32_e32 v6, -2.0, v6
	v_mul_f32_e32 v6, 0x3fb8aa3b, v6
	v_exp_f32_e32 v6, v6
	s_nop 0
	v_add_f32_e32 v6, 1.0, v6
	v_rcp_f32_e32 v6, v6
	s_nop 0
	v_mul_f32_e32 v69, v69, v6
	v_mul_f32_e32 v69, v22, v69
	v_mul_f32_e32 v69, v122, v69
	v_mul_f32_e32 v71, v71, v121
	v_mul_f32_e32 v7, 0x3d372713, v71
	v_mul_f32_e32 v7, v71, v7
	v_fma_f32 v7, v71, v7, v71
	v_mul_f32_e32 v7, 0x3f4c422a, v7
	v_mul_f32_e32 v7, -2.0, v7
	v_mul_f32_e32 v7, 0x3fb8aa3b, v7
	v_exp_f32_e32 v7, v7
	s_nop 0
	v_add_f32_e32 v7, 1.0, v7
	v_rcp_f32_e32 v7, v7
	s_nop 0
	v_mul_f32_e32 v71, v71, v7
	v_mul_f32_e32 v71, v23, v71
	v_mul_f32_e32 v71, v123, v71
	v_mov_b32_e32 v68, v20
	v_mov_b32_e32 v70, v21
	ds_write_b128 v3, v[68:71] offset:0
	s_waitcnt vmcnt(24)
	v_mul_f32_e32 v73, v73, v124
	v_mul_f32_e32 v6, 0x3d372713, v73
	v_mul_f32_e32 v6, v73, v6
	v_fma_f32 v6, v73, v6, v73
	v_mul_f32_e32 v6, 0x3f4c422a, v6
	v_mul_f32_e32 v6, -2.0, v6
	v_mul_f32_e32 v6, 0x3fb8aa3b, v6
	v_exp_f32_e32 v6, v6
	s_nop 0
	v_add_f32_e32 v6, 1.0, v6
	v_rcp_f32_e32 v6, v6
	s_nop 0
	v_mul_f32_e32 v73, v73, v6
	v_mul_f32_e32 v73, v26, v73
	v_mul_f32_e32 v73, v126, v73
	v_mul_f32_e32 v75, v75, v125
	v_mul_f32_e32 v7, 0x3d372713, v75
	v_mul_f32_e32 v7, v75, v7
	v_fma_f32 v7, v75, v7, v75
	v_mul_f32_e32 v7, 0x3f4c422a, v7
	v_mul_f32_e32 v7, -2.0, v7
	v_mul_f32_e32 v7, 0x3fb8aa3b, v7
	v_exp_f32_e32 v7, v7
	s_nop 0
	v_add_f32_e32 v7, 1.0, v7
	v_rcp_f32_e32 v7, v7
	s_nop 0
	v_mul_f32_e32 v75, v75, v7
	v_mul_f32_e32 v75, v27, v75
	v_mul_f32_e32 v75, v127, v75
	v_mov_b32_e32 v72, v24
	v_mov_b32_e32 v74, v25
	ds_write_b128 v3, v[72:75] offset:1024
	s_waitcnt vmcnt(20)
	v_mul_f32_e32 v77, v77, v128
	v_mul_f32_e32 v6, 0x3d372713, v77
	v_mul_f32_e32 v6, v77, v6
	v_fma_f32 v6, v77, v6, v77
	v_mul_f32_e32 v6, 0x3f4c422a, v6
	v_mul_f32_e32 v6, -2.0, v6
	v_mul_f32_e32 v6, 0x3fb8aa3b, v6
	v_exp_f32_e32 v6, v6
	s_nop 0
	v_add_f32_e32 v6, 1.0, v6
	v_rcp_f32_e32 v6, v6
	s_nop 0
	v_mul_f32_e32 v77, v77, v6
	v_mul_f32_e32 v77, v30, v77
	v_mul_f32_e32 v77, v130, v77
	v_mul_f32_e32 v79, v79, v129
	v_mul_f32_e32 v7, 0x3d372713, v79
	v_mul_f32_e32 v7, v79, v7
	v_fma_f32 v7, v79, v7, v79
	v_mul_f32_e32 v7, 0x3f4c422a, v7
	v_mul_f32_e32 v7, -2.0, v7
	v_mul_f32_e32 v7, 0x3fb8aa3b, v7
	v_exp_f32_e32 v7, v7
	s_nop 0
	v_add_f32_e32 v7, 1.0, v7
	v_rcp_f32_e32 v7, v7
	s_nop 0
	v_mul_f32_e32 v79, v79, v7
	v_mul_f32_e32 v79, v31, v79
	v_mul_f32_e32 v79, v131, v79
	v_mov_b32_e32 v76, v28
	v_mov_b32_e32 v78, v29
	ds_write_b128 v3, v[76:79] offset:2048
	s_waitcnt vmcnt(16)
	v_mul_f32_e32 v81, v81, v132
	v_mul_f32_e32 v6, 0x3d372713, v81
	v_mul_f32_e32 v6, v81, v6
	v_fma_f32 v6, v81, v6, v81
	v_mul_f32_e32 v6, 0x3f4c422a, v6
	v_mul_f32_e32 v6, -2.0, v6
	v_mul_f32_e32 v6, 0x3fb8aa3b, v6
	v_exp_f32_e32 v6, v6
	s_nop 0
	v_add_f32_e32 v6, 1.0, v6
	v_rcp_f32_e32 v6, v6
	s_nop 0
	v_mul_f32_e32 v81, v81, v6
	v_mul_f32_e32 v81, v34, v81
	v_mul_f32_e32 v81, v134, v81
	v_mul_f32_e32 v83, v83, v133
	v_mul_f32_e32 v7, 0x3d372713, v83
	v_mul_f32_e32 v7, v83, v7
	v_fma_f32 v7, v83, v7, v83
	v_mul_f32_e32 v7, 0x3f4c422a, v7
	v_mul_f32_e32 v7, -2.0, v7
	v_mul_f32_e32 v7, 0x3fb8aa3b, v7
	v_exp_f32_e32 v7, v7
	s_nop 0
	v_add_f32_e32 v7, 1.0, v7
	v_rcp_f32_e32 v7, v7
	s_nop 0
	v_mul_f32_e32 v83, v83, v7
	v_mul_f32_e32 v83, v35, v83
	v_mul_f32_e32 v83, v135, v83
	v_mov_b32_e32 v80, v32
	v_mov_b32_e32 v82, v33
	ds_write_b128 v3, v[80:83] offset:3072
	s_waitcnt vmcnt(12)
	v_mul_f32_e32 v85, v85, v136
	v_mul_f32_e32 v6, 0x3d372713, v85
	v_mul_f32_e32 v6, v85, v6
	v_fma_f32 v6, v85, v6, v85
	v_mul_f32_e32 v6, 0x3f4c422a, v6
	v_mul_f32_e32 v6, -2.0, v6
	v_mul_f32_e32 v6, 0x3fb8aa3b, v6
	v_exp_f32_e32 v6, v6
	s_nop 0
	v_add_f32_e32 v6, 1.0, v6
	v_rcp_f32_e32 v6, v6
	s_nop 0
	v_mul_f32_e32 v85, v85, v6
	v_mul_f32_e32 v85, v38, v85
	v_mul_f32_e32 v85, v138, v85
	v_mul_f32_e32 v87, v87, v137
	v_mul_f32_e32 v7, 0x3d372713, v87
	v_mul_f32_e32 v7, v87, v7
	v_fma_f32 v7, v87, v7, v87
	v_mul_f32_e32 v7, 0x3f4c422a, v7
	v_mul_f32_e32 v7, -2.0, v7
	v_mul_f32_e32 v7, 0x3fb8aa3b, v7
	v_exp_f32_e32 v7, v7
	s_nop 0
	v_add_f32_e32 v7, 1.0, v7
	v_rcp_f32_e32 v7, v7
	s_nop 0
	v_mul_f32_e32 v87, v87, v7
	v_mul_f32_e32 v87, v39, v87
	v_mul_f32_e32 v87, v139, v87
	v_mov_b32_e32 v84, v36
	v_mov_b32_e32 v86, v37
	ds_write_b128 v3, v[84:87] offset:4096
	s_waitcnt vmcnt(8)
; DEVI float gelu_f(float x) { const float u = 0.7978845608028654f * (x + 0.044715f * x * x * x); return x * __builtin_amdgcn_rcpf(1.f + __expf(-2.f * u)); }
;     ...
;     for (int t = 0; t < NTL; ++t) { const float lo = __shfl_xor(acc[t][0], 32); const float dot = (acc[t][0] + lo * (1.f / 32.f)) * s_u[t];
;         if (kq == 0) pl[t * 16 + n16] = (u32x2_t){(unsigned)e[t], __float_as_uint(g[t] * gelu_f(dot) * s_v[t])}; }
;     }
;     if (PART == 1) return;
;     float o[16];
; #pragma unroll
;     for (int i = 0; i < 16; ++i) o[i] = 0.f;
;     for (int j0 = 0; j0 < NTL * 16; j0 += 16) {
;         u32x4_t w[16]; float cj[16];
; #pragma unroll
;         for (int jj = 0; jj < 16; ++jj) { const u32x2_t pr = pl[j0 + jj]; const int ej = __builtin_amdgcn_readfirstlane((int)pr.x); cj[jj] = __uint_as_float(pr.y);
;             w[jj] = *(const u32x4_t*)(v8 + (size_t)ej * D + 16 * lane); }
	v_mul_f32_e32 v89, v89, v140
	v_mul_f32_e32 v6, 0x3d372713, v89
	v_mul_f32_e32 v6, v89, v6
	v_fma_f32 v6, v89, v6, v89
	v_mul_f32_e32 v6, 0x3f4c422a, v6
	v_mul_f32_e32 v6, -2.0, v6
	v_mul_f32_e32 v6, 0x3fb8aa3b, v6
	v_exp_f32_e32 v6, v6
	s_nop 0
	v_add_f32_e32 v6, 1.0, v6
	v_rcp_f32_e32 v6, v6
	s_nop 0
	v_mul_f32_e32 v89, v89, v6
	v_mul_f32_e32 v89, v42, v89
	v_mul_f32_e32 v89, v142, v89
	v_mul_f32_e32 v91, v91, v141
	v_mul_f32_e32 v7, 0x3d372713, v91
	v_mul_f32_e32 v7, v91, v7
	v_fma_f32 v7, v91, v7, v91
	v_mul_f32_e32 v7, 0x3f4c422a, v7
	v_mul_f32_e32 v7, -2.0, v7
	v_mul_f32_e32 v7, 0x3fb8aa3b, v7
	v_exp_f32_e32 v7, v7
	s_nop 0
	v_add_f32_e32 v7, 1.0, v7
	v_rcp_f32_e32 v7, v7
	s_nop 0
	v_mul_f32_e32 v91, v91, v7
	v_mul_f32_e32 v91, v43, v91
	v_mul_f32_e32 v91, v143, v91
	v_mov_b32_e32 v88, v40
	v_mov_b32_e32 v90, v41
	ds_write_b128 v3, v[88:91] offset:5120
	s_waitcnt vmcnt(4)
	v_mul_f32_e32 v93, v93, v144
	v_mul_f32_e32 v6, 0x3d372713, v93
	v_mul_f32_e32 v6, v93, v6
	v_fma_f32 v6, v93, v6, v93
	v_mul_f32_e32 v6, 0x3f4c422a, v6
	v_mul_f32_e32 v6, -2.0, v6
	v_mul_f32_e32 v6, 0x3fb8aa3b, v6
	v_exp_f32_e32 v6, v6
	s_nop 0
	v_add_f32_e32 v6, 1.0, v6
	v_rcp_f32_e32 v6, v6
	s_nop 0
	v_mul_f32_e32 v93, v93, v6
	v_mul_f32_e32 v93, v46, v93
	v_mul_f32_e32 v93, v146, v93
	v_mul_f32_e32 v95, v95, v145
	v_mul_f32_e32 v7, 0x3d372713, v95
	v_mul_f32_e32 v7, v95, v7
	v_fma_f32 v7, v95, v7, v95
	v_mul_f32_e32 v7, 0x3f4c422a, v7
	v_mul_f32_e32 v7, -2.0, v7
	v_mul_f32_e32 v7, 0x3fb8aa3b, v7
	v_exp_f32_e32 v7, v7
	s_nop 0
	v_add_f32_e32 v7, 1.0, v7
	v_rcp_f32_e32 v7, v7
	s_nop 0
	v_mul_f32_e32 v95, v95, v7
	v_mul_f32_e32 v95, v47, v95
	v_mul_f32_e32 v95, v147, v95
	v_mov_b32_e32 v92, v44
	v_mov_b32_e32 v94, v45
	ds_write_b128 v3, v[92:95] offset:6144
	s_waitcnt vmcnt(0)
	v_mul_f32_e32 v97, v97, v148
	v_mul_f32_e32 v6, 0x3d372713, v97
	v_mul_f32_e32 v6, v97, v6
	v_fma_f32 v6, v97, v6, v97
	v_mul_f32_e32 v6, 0x3f4c422a, v6
	v_mul_f32_e32 v6, -2.0, v6
	v_mul_f32_e32 v6, 0x3fb8aa3b, v6
	v_exp_f32_e32 v6, v6
	s_nop 0
	v_add_f32_e32 v6, 1.0, v6
	v_rcp_f32_e32 v6, v6
	s_nop 0
	v_mul_f32_e32 v97, v97, v6
	v_mul_f32_e32 v97, v50, v97
	v_mul_f32_e32 v97, v150, v97
	v_mul_f32_e32 v99, v99, v149
	v_mul_f32_e32 v7, 0x3d372713, v99
	v_mul_f32_e32 v7, v99, v7
	v_fma_f32 v7, v99, v7, v99
	v_mul_f32_e32 v7, 0x3f4c422a, v7
	v_mul_f32_e32 v7, -2.0, v7
	v_mul_f32_e32 v7, 0x3fb8aa3b, v7
	v_exp_f32_e32 v7, v7
	s_nop 0
	v_add_f32_e32 v7, 1.0, v7
	v_rcp_f32_e32 v7, v7
	s_nop 0
	v_mul_f32_e32 v99, v99, v7
	v_mul_f32_e32 v99, v51, v99
	v_mul_f32_e32 v99, v151, v99
	v_mov_b32_e32 v96, v48
	v_mov_b32_e32 v98, v49
	ds_write_b128 v3, v[96:99] offset:7168
	s_waitcnt lgkmcnt(0)
	v_cmp_gt_u32_e32 vcc, 8, v116
	s_nop 1
	s_lshl_b32 s20, s34, 12
	s_lshl_b32 s11, s8, 24
	s_add_u32 s56, s6, 0x27a42100
	s_addc_u32 s57, s7, 0
	s_add_u32 s56, s56, s11
	s_addc_u32 s57, s57, 0
	s_mov_b32 s12, s56
	s_mov_b32 s13, s57
	s_lshl_b32 s11, s48, 12
	s_add_u32 s58, s4, s11
	s_addc_u32 s59, s5, 0
	s_mul_i32 s11, s8, 0x6c000
	s_add_u32 s60, s6, 0x9000
	s_addc_u32 s61, s7, 0
	s_add_u32 s60, s60, s11
	s_addc_u32 s61, s61, 0
	s_mov_b32 s24, 0xff00ff00
	s_mov_b32 s25, 0xff00ff00
	v_and_b32_e32 v2, 7, v1
	v_lshrrev_b32_e32 v3, 3, v1
	v_lshlrev_b32_e32 v4, 4, v2
	v_lshlrev_b32_e32 v5, 7, v3
	v_add_u32_e32 v5, s85, v5
	v_lshlrev_b32_e32 v6, 6, v2
	v_lshl_add_u32 v6, v3, 3, v6
	ds_read_b128 v[26:29], v5 offset:0
	ds_read_b128 v[30:33], v5 offset:16
	ds_read_b128 v[34:37], v5 offset:32
	ds_read_b128 v[38:41], v5 offset:48
	ds_read_b128 v[42:45], v5 offset:64
	ds_read_b128 v[46:49], v5 offset:80
	ds_read_b128 v[50:53], v5 offset:96
	ds_read_b128 v[54:57], v5 offset:112
	s_waitcnt lgkmcnt(0)
	v_lshl_add_u32 v68, v26, 10, v4
	v_lshl_add_u32 v69, v28, 10, v4
	v_lshl_add_u32 v70, v30, 10, v4
	v_lshl_add_u32 v71, v32, 10, v4
	v_lshl_add_u32 v72, v34, 10, v4
	v_lshl_add_u32 v73, v36, 10, v4
	v_lshl_add_u32 v74, v38, 10, v4
	v_lshl_add_u32 v75, v40, 10, v4
	v_lshl_add_u32 v76, v42, 10, v4
	v_lshl_add_u32 v77, v44, 10, v4
	v_lshl_add_u32 v78, v46, 10, v4
	v_lshl_add_u32 v79, v48, 10, v4
	v_lshl_add_u32 v80, v50, 10, v4
	v_lshl_add_u32 v81, v52, 10, v4
	v_lshl_add_u32 v82, v54, 10, v4
	v_lshl_add_u32 v83, v56, 10, v4
	global_load_dwordx4 v[120:123], v68, s[12:13]
	global_load_dwordx4 v[124:127], v69, s[12:13]
	global_load_dwordx4 v[128:131], v70, s[12:13]
	global_load_dwordx4 v[132:135], v71, s[12:13]
	global_load_dwordx4 v[136:139], v72, s[12:13]
	global_load_dwordx4 v[140:143], v73, s[12:13]
	global_load_dwordx4 v[144:147], v74, s[12:13]
	global_load_dwordx4 v[148:151], v75, s[12:13]
	global_load_dwordx4 v[152:155], v76, s[12:13]
	global_load_dwordx4 v[156:159], v77, s[12:13]
	global_load_dwordx4 v[160:163], v78, s[12:13]
	global_load_dwordx4 v[164:167], v79, s[12:13]
	global_load_dwordx4 v[168:171], v80, s[12:13]
	global_load_dwordx4 v[172:175], v81, s[12:13]
	global_load_dwordx4 v[188:191], v82, s[12:13]
	global_load_dwordx4 v[192:195], v83, s[12:13]
	s_mov_b32 s22, 0
